# hazard fix: s_nop 1 between v_cmp (vcc) and v_cndmask in the EpiQ loop; otherwise identical to the two-row conv version
# speedup vs baseline: 1.0030x; 1.0030x over previous
.Lq_norota:
	s_or_b64 exec, exec, s[10:11]
	v_mov_b32_e32 v28, v13
	v_mov_b32_e32 v29, v14
	v_mov_b32_e32 v13, v15
	v_pk_add_f32 v[12:13], v[28:29], v[12:13]
	v_add_f32_e32 v14, v16, v17
	v_pk_add_f32 v[12:13], v[12:13], v[12:13] op_sel:[0,1] op_sel_hi:[1,0]
	v_add_f32_e32 v16, v18, v19
	v_mov_b32_e32 v13, v8
	v_mov_b32_e32 v133, v9
	v_mov_b32_e32 v15, v10
	v_mov_b32_e32 v17, v11
	v_pk_add_f32 v[8:9], v[12:13], v[132:133]
	v_pk_add_f32 v[10:11], v[14:15], v[16:17]
	v_pk_add_f32 v[8:9], v[8:9], v[10:11]
	v_add_f32_e32 v8, v8, v9
	v_fmamk_f32 v8, v8, 0x3b2aaaab, v152
	v_mul_f32_e32 v9, 0x4b800000, v8
	v_cmp_gt_f32_e32 vcc, s68, v8
	s_nop 1
	v_cndmask_b32_e32 v8, v8, v9, vcc
	v_rsq_f32_e32 v8, v8
	s_nop 0
	v_mul_f32_e32 v9, 0x45800000, v8
	v_cndmask_b32_e32 v8, v8, v9, vcc
	v_mul_f32_e32 v8, 0x3e16c740, v8
	v_pk_mul_f32 v[0:1], v[8:9], v[0:1] op_sel_hi:[0,1]
	v_pk_mul_f32 v[2:3], v[8:9], v[2:3] op_sel_hi:[0,1]
	v_pk_mul_f32 v[4:5], v[8:9], v[4:5] op_sel_hi:[0,1]
	v_pk_mul_f32 v[6:7], v[8:9], v[6:7] op_sel_hi:[0,1]
	v_cvt_pk_bf16_f32 v0, v0, v1
	v_cvt_pk_bf16_f32 v1, v2, v3
	v_cvt_pk_bf16_f32 v2, v4, v5
	v_cvt_pk_bf16_f32 v3, v6, v7
	v_lshl_add_u64 v[4:5], s[26:27], 0, v[20:21]
	v_lshl_add_u64 v[20:21], v[20:21], 0, s[46:47]
	global_store_dwordx4 v[4:5], v[0:3], off
	s_addk_i32 s28, 0x2100
	s_cmp_eq_u32 s28, 0x1ef00
	s_cbranch_scc1 .Lq_last
	v_add_u32_e32 v80, 0x2c00000, v22
	v_add_u32_e32 v81, 0x2c80000, v22
	v_add_u32_e32 v82, 0x2d00000, v22
	v_add_u32_e32 v83, 0x2a00000, v24
	v_add_u32_e32 v84, 0x2800000, v24
	global_load_dwordx4 v[12:15], v80, s[26:27]
	global_load_dwordx4 v[16:19], v81, s[26:27]
	global_load_dwordx4 v[8:11], v82, s[26:27]
	global_load_dwordx4 v[28:31], v83, s[26:27]
	global_load_dwordx4 v[32:35], v83, s[26:27] offset:16
	global_load_dwordx4 v[36:39], v84, s[26:27]
	global_load_dwordx4 v[40:43], v84, s[26:27] offset:16
	v_add_u32_e32 v22, 0x100, v22
	v_add_u32_e32 v24, 0x400, v24
	v_add_u32_e32 v85, s28, v151
	ds_read_b128 v[4:7], v85
	v_add_u32_e32 v85, s28, v26
	ds_read_b128 v[44:47], v85
	s_waitcnt vmcnt(7)
	s_branch .Lq_c2

.Lq_norotb:
	s_or_b64 exec, exec, s[10:11]
	v_mov_b32_e32 v64, v57
	v_mov_b32_e32 v65, v58
	v_mov_b32_e32 v57, v59
	v_pk_add_f32 v[56:57], v[64:65], v[56:57]
	v_add_f32_e32 v58, v60, v61
	v_pk_add_f32 v[56:57], v[56:57], v[56:57] op_sel:[0,1] op_sel_hi:[1,0]
	v_add_f32_e32 v60, v62, v63
	v_mov_b32_e32 v57, v52
	v_mov_b32_e32 v133, v53
	v_mov_b32_e32 v59, v54
	v_mov_b32_e32 v61, v55
	v_pk_add_f32 v[52:53], v[56:57], v[132:133]
	v_pk_add_f32 v[54:55], v[58:59], v[60:61]
	v_pk_add_f32 v[52:53], v[52:53], v[54:55]
	v_add_f32_e32 v52, v52, v53
	v_fmamk_f32 v52, v52, 0x3b2aaaab, v152
	v_mul_f32_e32 v53, 0x4b800000, v52
	v_cmp_gt_f32_e32 vcc, s68, v52
	s_nop 1
	v_cndmask_b32_e32 v52, v52, v53, vcc
	v_rsq_f32_e32 v52, v52
	s_nop 0
	v_mul_f32_e32 v53, 0x45800000, v52
	v_cndmask_b32_e32 v52, v52, v53, vcc
	v_mul_f32_e32 v52, 0x3e16c740, v52
	v_pk_mul_f32 v[0:1], v[52:53], v[0:1] op_sel_hi:[0,1]
	v_pk_mul_f32 v[2:3], v[52:53], v[2:3] op_sel_hi:[0,1]
	v_pk_mul_f32 v[4:5], v[52:53], v[4:5] op_sel_hi:[0,1]
	v_pk_mul_f32 v[6:7], v[52:53], v[6:7] op_sel_hi:[0,1]
	v_cvt_pk_bf16_f32 v0, v0, v1
	v_cvt_pk_bf16_f32 v1, v2, v3
	v_cvt_pk_bf16_f32 v2, v4, v5
	v_cvt_pk_bf16_f32 v3, v6, v7
	v_lshl_add_u64 v[4:5], s[26:27], 0, v[20:21]
	v_lshl_add_u64 v[20:21], v[20:21], 0, s[46:47]
	global_store_dwordx4 v[4:5], v[0:3], off
	s_addk_i32 s28, 0x2100
	s_cmp_lg_u32 s28, 0x21000
	s_cbranch_scc1 .LBB0_430
	s_branch .LBB0_418
